# strategy 5 direct HBM->LDS loads: gemm_f32 k-tiles staged with global_load_lds_dwordx4 (M0 destination, source-side XOR swizzle) instead of register staging + ds_write
# baseline (speedup 1.0000x reference)
; #define RTID opaque_tid()
; template <int MI, int NJ> ...
;     ...
;   u16* sA = smem;
;   u16* sB = smem + 2 * AROWS * 64;
;   const int lrow = tid >> 3, lkc = tid & 7;
;   const u16* Ag = A + (size_t)(row0 + lrow) * lda + kbeg + lkc * 8;
;   const u16* Bg = Bt + (size_t)(col0 + lrow) * ldb + kbeg + lkc * 8;
;   const size_t a64 = (size_t)64 * lda, b64 = (size_t)64 * ldb;
;   const int nk = (kend - kbeg) >> 6;
;   const long long nAoff = (long long)(nrow0 - row0) * lda + (nkbeg - kbeg);
;   const long long nBoff = (long long)(ncol0 - col0) * ldb + (nkbeg - kbeg);
;   u16* wa = sA + lrow * 64 + ((lkc ^ (lrow & 7)) * 8);
;   u16* wb = sB + lrow * 64 + ((lkc ^ (lrow & 7)) * 8);
; __device__ __forceinline__ void phase_gemm_f32(const u16* A, const u16* Bt, int K, u16* out, u16* smem,
;                                                volatile LAS unsigned* vb_) {
;   const int tid = RTID;
;   const int lane = tid & 63, wave = tid >> 6;
;   const int wm = wave >> 2, wn = wave & 3;
;   const int vb = real_vb(vb_);
;   G8REGS_DECL;
;   R_b1 = R_b2 = R_b3 = make_uint4(0u, 0u, 0u, 0u);
;   const int step = gridDim.x >> 3;
.LBB0_475:
	s_nop 0
	v_readlane_b32 s0, v255, 4
	v_readlane_b32 s1, v255, 5
	s_and_b64 vcc, exec, s[0:1]
	s_cbranch_vccz .LBB0_484
	s_waitcnt vmcnt(15)
	v_mov_b32_e32 v2, v175
	ds_read_b32 v0, v230
	s_waitcnt lgkmcnt(0)
	v_readfirstlane_b32 s0, v0
	s_ashr_i32 s37, s0, 3
	s_cmp_gt_i32 s37, 31
	s_cbranch_scc1 .LBB0_483
	s_cmp_eq_u32 s82, 10
	s_movk_i32 s1, 0xb00
	s_cselect_b32 s10, 0x400, s1
	s_mov_b32 s1, 0x3810000
	s_cselect_b32 s1, s1, 0x5810000
	s_cmp_eq_u32 s82, 1
	s_mov_b32 s11, 0xb00000
	s_cselect_b32 s11, s11, 0x1b80000
	s_cmp_eq_u32 s82, 10
	s_mov_b32 s12, 0xf010000
	s_cselect_b32 s12, s12, 0xb010000
	s_cselect_b32 s13, 0x3400000, s11
	s_add_u32 s11, s72, s12
	s_addc_u32 s20, s73, 0
	s_add_u32 s12, s72, s13
	s_addc_u32 s13, s73, 0
	s_add_u32 s38, s72, s1
	v_lshlrev_b32_e32 v0, 4, v2
	s_addc_u32 s39, s73, 0
	v_ashrrev_i32_e32 v184, 3, v2
	v_and_b32_e32 v0, 0x70, v0
	v_and_b32_e32 v234, 7, v184
	s_lshl_b32 s48, s10, 1
	s_lshl_b32 s49, s10, 7
	v_mul_lo_u32 v234, v234, s48
	v_and_b32_e32 v235, 7, v184
	v_lshlrev_b32_e32 v235, 4, v235
	v_xor_b32_e32 v235, v235, v0
	v_add_u32_e32 v234, v234, v235
	v_lshrrev_b32_e32 v235, 6, v175
	s_nop 0
	v_readfirstlane_b32 s66, v235
	s_lshl_b32 s66, s66, 10
	v_add_u32_e32 v235, s49, v234
	v_add_u32_e32 v236, s49, v235
	v_add_u32_e32 v237, s49, v236
	v_lshl_add_u64 v[176:177], s[38:39], 0, v[0:1]
	v_lshl_add_u64 v[178:179], s[12:13], 0, v[0:1]
	v_xor_b32_e32 v0, v184, v2
	v_lshlrev_b32_e32 v0, 4, v0
	v_and_b32_e32 v0, 0x70, v0
	v_lshl_or_b32 v185, v184, 7, v0
	v_lshrrev_b32_e32 v0, 4, v2
	v_and_b32_e32 v3, 7, v2
	v_bitop3_b32 v0, v0, v3, 3 bitop3:0x6c
	v_lshlrev_b32_e32 v3, 3, v0
	v_xor_b32_e32 v4, 32, v3
	v_sub_u32_e32 v3, v4, v3
	v_ashrrev_i32_e32 v4, 1, v2
	v_and_b32_e32 v4, 0xffffff80, v4
	v_and_or_b32 v5, v2, 15, v4
	v_lshlrev_b32_e32 v0, 4, v0
	s_lshl_b32 s0, s0, 3
	v_lshl_or_b32 v187, v5, 7, v0
	v_lshlrev_b32_e32 v5, 7, v2
	s_and_b32 s22, s0, 56
	v_and_b32_e32 v5, 0x6780, v5
	s_mov_b32 s0, 0x10000
	v_or3_b32 v188, v5, v0, s0
	v_lshrrev_b32_e32 v0, 2, v2
	v_and_or_b32 v0, v0, 12, v4
	v_and_b32_e32 v2, 0xcf, v2
	v_mul_lo_u32 v0, v0, s2
	s_lshl_b32 s23, s10, 6
	v_lshl_add_u32 v189, v2, 1, v0
	v_mov_b32_e32 v0, v1
	s_lshr_b32 s21, s10, 6
	v_add_u32_e32 v186, 0x10000, v185
	s_lshl_b32 s0, s10, 7
	s_mov_b32 s1, s59
	s_mov_b64 s[12:13], 0
	s_lshl_b32 s58, s23, 1
	v_lshlrev_b32_e32 v190, 1, v3
	s_waitcnt vmcnt(6)
	v_mov_b64_e32 v[42:43], v[0:1]
	v_mov_b64_e32 v[44:45], v[0:1]
	v_mov_b64_e32 v[62:63], v[0:1]
	v_mov_b64_e32 v[64:65], v[0:1]
	v_mov_b64_e32 v[74:75], v[0:1]
	v_mov_b64_e32 v[76:77], v[0:1]

; #define ZERO_ACC8(acc, NJ_)                             \
;   _Pragma("unroll") for (int i_ = 0; i_ < 8; ++i_)      \
;   _Pragma("unroll") for (int j_ = 0; j_ < (NJ_); ++j_) { acc[i_][j_] = (f32x4){0.f, 0.f, 0.f, 0.f}; }
; template <int MI, int NJ> ...
;     ...
;   if (!pre) G8LOADP(Ag, Bg);
;   G8STORE(0);
;   {
;     const u16* ga_ = (1 < nk) ? Ag + 64 : Ag + nAoff;
;     const u16* gb_ = (1 < nk) ? Bg + 64 : Bg + nBoff;
;     G8LOADP(ga_, gb_);
;   }
;   __syncthreads();
;   const int sw0 = ((lane >> 4) ^ (lane & 7)) * 8;
;   const int dsw = (sw0 ^ 32) - sw0;
;   const u16* ra_ = sA + (wm * (16 * MI) + (lane & 15)) * 64 + sw0;
;   const u16* rb_ = sB + (wn * (16 * NJ) + (lane & 15)) * 64 + sw0;
;   for (int kt = 0; kt < nk; ++kt) {
;     const int buf = kt & 1;
;     {
;       G8STORE(buf ^ 1);
;       const u16* ga_ = (kt + 2 < nk) ? Ag + (kt + 2) * 64 : Ag + nAoff;
;       const u16* gb_ = (kt + 2 < nk) ? Bg + (kt + 2) * 64 : Bg + nBoff;
;       G8LOADP(ga_, gb_);
;     }
; __device__ __forceinline__ void phase_gemm_f32(const u16* A, const u16* Bt, int K, u16* out, u16* smem,
;                                                volatile LAS unsigned* vb_) {
;     ...
;   for (int lt = vb >> 3; lt < 8 * 4; lt += step) {
;     const int nt = lt >> 3, mt = (vb & 7) * 8 + (lt & 7);
;     const int ltn = (lt + step < 8 * 4) ? lt + step : lt;
;     f32x4 acc[8][4];
;     ZERO_ACC8(acc, 4);
;     gemm8<8, 4>(acc, G8REGS_ARGS, pre, A, K, Bt, K, 0, K, mt * 256, nt * 256, ((vb & 7) * 8 + (ltn & 7)) * 256, (ltn >> 3) * 256, 0, smem, tid);
.LBB0_480:
	s_add_u32 s50, s62, 0x80
	s_addc_u32 s51, s63, 0
	s_add_u32 s52, s64, 0x80
	s_addc_u32 s53, s65, 0
	s_mov_b32 m0, s66
	s_nop 0
	global_load_lds_dwordx4 v234, s[62:63]
	s_add_u32 m0, s66, 0x2000
	s_nop 0
	global_load_lds_dwordx4 v235, s[62:63]
	s_add_u32 m0, s66, 0x4000
	s_nop 0
	global_load_lds_dwordx4 v236, s[62:63]
	s_add_u32 m0, s66, 0x6000
	s_nop 0
	global_load_lds_dwordx4 v237, s[62:63]
	s_add_u32 m0, s66, 0x10000
	s_nop 0
	global_load_lds_dwordx4 v234, s[64:65]
	s_add_u32 m0, s66, 0x12000
	s_nop 0
	global_load_lds_dwordx4 v235, s[64:65]
	s_add_u32 m0, s66, 0x14000
	s_nop 0
	global_load_lds_dwordx4 v236, s[64:65]
	s_add_u32 m0, s66, 0x16000
	s_nop 0
	global_load_lds_dwordx4 v237, s[64:65]
	s_add_u32 m0, s66, 0x8000
	s_nop 0
	global_load_lds_dwordx4 v234, s[50:51]
	s_add_u32 m0, s66, 0xa000
	s_nop 0
	global_load_lds_dwordx4 v235, s[50:51]
	s_add_u32 m0, s66, 0xc000
	s_nop 0
	global_load_lds_dwordx4 v236, s[50:51]
	s_add_u32 m0, s66, 0xe000
	s_nop 0
	global_load_lds_dwordx4 v237, s[50:51]
	s_add_u32 m0, s66, 0x18000
	s_nop 0
	global_load_lds_dwordx4 v234, s[52:53]
	s_add_u32 m0, s66, 0x1a000
	s_nop 0
	global_load_lds_dwordx4 v235, s[52:53]
	s_add_u32 m0, s66, 0x1c000
	s_nop 0
	global_load_lds_dwordx4 v236, s[52:53]
	s_add_u32 m0, s66, 0x1e000
	s_nop 0
	global_load_lds_dwordx4 v237, s[52:53]
	s_waitcnt vmcnt(0)
.Lk1done_gf32:
	s_add_i32 s36, s37, s70
	s_cmp_gt_i32 s36, 31
	s_cselect_b64 s[40:41], -1, 0
	s_cmp_lt_i32 s36, 32
	s_cselect_b32 s12, s36, s37
	s_and_b32 s13, s12, 7
	s_lshl_b32 s12, s12, 5
	s_and_b32 s37, s12, 0xffffff00
	s_sub_i32 s12, s13, s38
	s_lshl_b32 s13, s12, 8
	s_sub_i32 s38, s37, s42
	v_mov_b32_e32 v22, 0
	s_mul_hi_i32 s12, s13, s10
	s_mul_i32 s13, s13, s10
	s_mul_hi_i32 s37, s38, s10
	s_mul_i32 s38, s38, s10
	s_movk_i32 s39, 0x80
	s_mov_b32 s43, 0
	s_mov_b32 s44, 0
	v_mov_b32_e32 v23, v22
	v_mov_b32_e32 v24, v22
	v_mov_b32_e32 v25, v22
	v_mov_b32_e32 v26, v22
	v_mov_b32_e32 v27, v22
	v_mov_b32_e32 v28, v22
	v_mov_b32_e32 v29, v22
	v_mov_b32_e32 v30, v22
	v_mov_b32_e32 v31, v22
	v_mov_b32_e32 v32, v22
	v_mov_b32_e32 v33, v22
	v_mov_b32_e32 v34, v22
	v_mov_b32_e32 v35, v22
	v_mov_b32_e32 v36, v22
	v_mov_b32_e32 v37, v22
	v_mov_b32_e32 v38, v22
	v_mov_b32_e32 v39, v22
	v_mov_b32_e32 v40, v22
	v_mov_b32_e32 v41, v22
	v_mov_b32_e32 v46, v22
	v_mov_b32_e32 v47, v22
	v_mov_b32_e32 v48, v22
	v_mov_b32_e32 v49, v22
	v_mov_b32_e32 v50, v22
	v_mov_b32_e32 v51, v22
	v_mov_b32_e32 v52, v22
	v_mov_b32_e32 v53, v22
	v_mov_b32_e32 v54, v22
	v_mov_b32_e32 v55, v22
	v_mov_b32_e32 v56, v22
	v_mov_b32_e32 v57, v22
	v_mov_b32_e32 v58, v22
	v_mov_b32_e32 v59, v22
	v_mov_b32_e32 v60, v22
	v_mov_b32_e32 v61, v22
	v_mov_b32_e32 v66, v22
	v_mov_b32_e32 v67, v22
	v_mov_b32_e32 v68, v22
	v_mov_b32_e32 v69, v22
	v_mov_b32_e32 v70, v22
	v_mov_b32_e32 v71, v22
	v_mov_b32_e32 v72, v22
	v_mov_b32_e32 v73, v22
	v_mov_b32_e32 v78, v22
	v_mov_b32_e32 v79, v22
	v_mov_b32_e32 v80, v22
	v_mov_b32_e32 v81, v22
	v_mov_b32_e32 v82, v22
	v_mov_b32_e32 v83, v22
	v_mov_b32_e32 v84, v22
	v_mov_b32_e32 v85, v22
	v_mov_b32_e32 v86, v22
	v_mov_b32_e32 v87, v22
	v_mov_b32_e32 v88, v22
	v_mov_b32_e32 v89, v22
	v_mov_b32_e32 v90, v22
	v_mov_b32_e32 v91, v22
	v_mov_b32_e32 v92, v22
	v_mov_b32_e32 v93, v22
	v_mov_b32_e32 v94, v22
	v_mov_b32_e32 v95, v22
	v_mov_b32_e32 v96, v22
	v_mov_b32_e32 v97, v22
	v_mov_b32_e32 v98, v22
	v_mov_b32_e32 v99, v22
	v_mov_b32_e32 v100, v22
	v_mov_b32_e32 v101, v22
	v_mov_b32_e32 v102, v22
	v_mov_b32_e32 v103, v22
	v_mov_b32_e32 v104, v22
	v_mov_b32_e32 v105, v22
	v_mov_b32_e32 v106, v22
	v_mov_b32_e32 v107, v22
	v_mov_b32_e32 v108, v22
	v_mov_b32_e32 v109, v22
	v_mov_b32_e32 v110, v22
	v_mov_b32_e32 v111, v22
	v_mov_b32_e32 v112, v22
	v_mov_b32_e32 v113, v22
	v_mov_b32_e32 v114, v22
	v_mov_b32_e32 v115, v22
	v_mov_b32_e32 v116, v22
	v_mov_b32_e32 v117, v22
	v_mov_b32_e32 v118, v22
	v_mov_b32_e32 v119, v22
	v_mov_b32_e32 v120, v22
	v_mov_b32_e32 v121, v22
	v_mov_b32_e32 v122, v22
	v_mov_b32_e32 v123, v22
	v_mov_b32_e32 v124, v22
	v_mov_b32_e32 v125, v22
	v_mov_b32_e32 v126, v22
	v_mov_b32_e32 v127, v22
	v_mov_b32_e32 v128, v22
	v_mov_b32_e32 v129, v22
	v_mov_b32_e32 v130, v22
	v_mov_b32_e32 v131, v22
	v_mov_b32_e32 v132, v22
	v_mov_b32_e32 v133, v22
	v_mov_b32_e32 v134, v22
	v_mov_b32_e32 v135, v22
	v_mov_b32_e32 v136, v22
	v_mov_b32_e32 v137, v22
	v_mov_b32_e32 v138, v22
	v_mov_b32_e32 v139, v22
	v_mov_b32_e32 v140, v22
	v_mov_b32_e32 v141, v22
	v_mov_b32_e32 v142, v22
	v_mov_b32_e32 v143, v22
	v_mov_b32_e32 v144, v22
	v_mov_b32_e32 v145, v22
	v_mov_b32_e32 v146, v22
	v_mov_b32_e32 v147, v22
	v_mov_b32_e32 v148, v22
	v_mov_b32_e32 v149, v22
	v_mov_b32_e32 v150, v22
	v_mov_b32_e32 v151, v22
	v_mov_b32_e32 v152, v22
	v_mov_b32_e32 v153, v22
	v_mov_b32_e32 v154, v22
	v_mov_b32_e32 v155, v22
	v_mov_b32_e32 v156, v22
	v_mov_b32_e32 v157, v22
	v_mov_b32_e32 v158, v22
	v_mov_b32_e32 v159, v22
	v_mov_b32_e32 v160, v22
	v_mov_b32_e32 v161, v22
	s_waitcnt lgkmcnt(0)
	s_barrier
	s_and_b32 s45, s43, 0x4000
	s_sub_i32 s67, s39, 64
	s_add_i32 s46, s44, 1
	s_cmp_lt_u32 s46, s21
	s_cselect_b32 s47, 0, s12
	s_cselect_b32 s46, s67, s13
	s_cselect_b32 s49, 0, s37
	s_cselect_b32 s48, s67, s38
	s_lshl_b64 s[46:47], s[46:47], 1
	s_lshl_b64 s[48:49], s[48:49], 1
	s_add_u32 s50, s62, s46
	s_addc_u32 s51, s63, s47
	s_add_u32 s52, s64, s48
	s_addc_u32 s53, s65, s49
	s_lshl_b32 s45, s45, 1
	v_add_u32_e32 v0, s45, v187
	v_add_u32_e32 v191, s45, v188
	ds_read_b128 v[166:169], v191
	ds_read_b128 v[162:165], v0
	ds_read_b128 v[170:173], v191 offset:2048
	ds_read_b128 v[192:195], v191 offset:4096
	ds_read_b128 v[196:199], v191 offset:6144
	ds_read_b128 v[204:207], v0 offset:2048
	ds_read_b128 v[208:211], v0 offset:4096
	ds_read_b128 v[238:241], v0 offset:6144
	v_add_u32_e32 v191, v191, v190
; template <int MI, int NJ> ...
;     ...
;   for (int kt = 0; kt < nk; ++kt) {
;     const int buf = kt & 1;
;     {
;       G8STORE(buf ^ 1);
;       const u16* ga_ = (kt + 2 < nk) ? Ag + (kt + 2) * 64 : Ag + nAoff;
;       const u16* gb_ = (kt + 2 < nk) ? Bg + (kt + 2) * 64 : Bg + nBoff;
;       G8LOADP(ga_, gb_);
;     }
;     __builtin_amdgcn_sched_barrier(0);
;     __builtin_amdgcn_s_setprio(1);
;     const u16* a = ra_ + buf * AROWS * 64;
;     const u16* b = rb_ + buf * BROWS * 64;
; #pragma unroll
;     for (int ks = 0; ks < 2; ++ks) {
;       const u16* a_ = ks ? a + dsw : a;
;       const u16* b_ = ks ? b + dsw : b;
;       bf16x8 bfr[NJ];
; #pragma unroll
;       for (int j = 0; j < NJ; ++j) bfr[j] = *(const bf16x8*)(b_ + j * 16 * 64);
; #pragma unroll
;       for (int ih = 0; ih < MI / 4; ++ih) {
;         bf16x8 af[4];
; #pragma unroll
;         for (int i = 0; i < 4; ++i) af[i] = *(const bf16x8*)(a_ + (ih * 4 + i) * 16 * 64);
; #pragma unroll
;         for (int i = 0; i < 4; ++i)
; #pragma unroll
;           for (int j = 0; j < NJ; ++j) acc[ih * 4 + i][j] = mfma16(af[i], bfr[j], acc[ih * 4 + i][j]);
;       }
;     }
;     __builtin_amdgcn_s_setprio(0);
;     __builtin_amdgcn_sched_barrier(0);
;     __syncthreads();
.LBB0_481:
	s_add_i32 s67, s44, 1
	s_and_b32 s67, s67, 1
	s_lshl_b32 s67, s67, 15
	s_add_u32 s67, s67, s66
	s_setprio 1
	s_waitcnt lgkmcnt(6)
	v_mfma_f32_16x16x32_bf16 v[158:161], v[166:169], v[162:165], v[158:161]
	s_waitcnt lgkmcnt(5)
	v_mfma_f32_16x16x32_bf16 v[154:157], v[170:173], v[162:165], v[154:157]
	s_waitcnt lgkmcnt(4)
	v_mfma_f32_16x16x32_bf16 v[150:153], v[192:195], v[162:165], v[150:153]
	s_waitcnt lgkmcnt(3)
	v_mfma_f32_16x16x32_bf16 v[146:149], v[196:199], v[162:165], v[146:149]
	ds_read_b128 v[162:165], v0 offset:8192
	s_mov_b32 m0, s67
	s_nop 0
	global_load_lds_dwordx4 v234, s[50:51]
	s_add_u32 m0, s67, 0x2000
	s_nop 0
	global_load_lds_dwordx4 v235, s[50:51]
	s_add_u32 m0, s67, 0x4000
	s_nop 0
	global_load_lds_dwordx4 v236, s[50:51]
	s_add_u32 m0, s67, 0x6000
	s_nop 0
	global_load_lds_dwordx4 v237, s[50:51]
	s_waitcnt lgkmcnt(3)
	v_mfma_f32_16x16x32_bf16 v[142:145], v[166:169], v[204:207], v[142:145]
	v_mfma_f32_16x16x32_bf16 v[138:141], v[170:173], v[204:207], v[138:141]
	v_mfma_f32_16x16x32_bf16 v[134:137], v[192:195], v[204:207], v[134:137]
	v_mfma_f32_16x16x32_bf16 v[130:133], v[196:199], v[204:207], v[130:133]
	ds_read_b128 v[204:207], v0 offset:10240
	s_add_u32 m0, s67, 0x10000
	s_nop 0
	global_load_lds_dwordx4 v234, s[52:53]
	s_add_u32 m0, s67, 0x12000
	s_nop 0
	global_load_lds_dwordx4 v235, s[52:53]
	s_add_u32 m0, s67, 0x14000
	s_nop 0
	global_load_lds_dwordx4 v236, s[52:53]
	s_add_u32 m0, s67, 0x16000
	s_nop 0
	global_load_lds_dwordx4 v237, s[52:53]
	s_waitcnt lgkmcnt(3)
	v_mfma_f32_16x16x32_bf16 v[126:129], v[166:169], v[208:211], v[126:129]
	v_mfma_f32_16x16x32_bf16 v[122:125], v[170:173], v[208:211], v[122:125]
	v_mfma_f32_16x16x32_bf16 v[118:121], v[192:195], v[208:211], v[118:121]
	v_mfma_f32_16x16x32_bf16 v[114:117], v[196:199], v[208:211], v[114:117]
	ds_read_b128 v[208:211], v0 offset:12288
	ds_read_b128 v[212:215], v191
	ds_read_b128 v[216:219], v191 offset:2048
	s_waitcnt lgkmcnt(5)
	v_mfma_f32_16x16x32_bf16 v[110:113], v[166:169], v[238:241], v[110:113]
	v_mfma_f32_16x16x32_bf16 v[106:109], v[170:173], v[238:241], v[106:109]
	v_mfma_f32_16x16x32_bf16 v[102:105], v[192:195], v[238:241], v[102:105]
	v_mfma_f32_16x16x32_bf16 v[98:101], v[196:199], v[238:241], v[98:101]
	ds_read_b128 v[238:241], v0 offset:14336
	ds_read_b128 v[220:223], v191 offset:4096
	ds_read_b128 v[224:227], v191 offset:6144
	s_waitcnt lgkmcnt(7)
	v_mfma_f32_16x16x32_bf16 v[94:97], v[166:169], v[162:165], v[94:97]
	v_mfma_f32_16x16x32_bf16 v[90:93], v[170:173], v[162:165], v[90:93]
	v_mfma_f32_16x16x32_bf16 v[86:89], v[192:195], v[162:165], v[86:89]
	v_mfma_f32_16x16x32_bf16 v[82:85], v[196:199], v[162:165], v[82:85]
	v_add_u32_e32 v0, v0, v190
	ds_read_b128 v[162:165], v0
	s_waitcnt lgkmcnt(7)
	v_mfma_f32_16x16x32_bf16 v[78:81], v[166:169], v[204:207], v[78:81]
	v_mfma_f32_16x16x32_bf16 v[70:73], v[170:173], v[204:207], v[70:73]
	v_mfma_f32_16x16x32_bf16 v[66:69], v[192:195], v[204:207], v[66:69]
	v_mfma_f32_16x16x32_bf16 v[58:61], v[196:199], v[204:207], v[58:61]
	ds_read_b128 v[204:207], v0 offset:2048
	s_waitcnt lgkmcnt(7)
	v_mfma_f32_16x16x32_bf16 v[54:57], v[166:169], v[208:211], v[54:57]
	v_mfma_f32_16x16x32_bf16 v[50:53], v[170:173], v[208:211], v[50:53]
	v_mfma_f32_16x16x32_bf16 v[46:49], v[192:195], v[208:211], v[46:49]
	v_mfma_f32_16x16x32_bf16 v[38:41], v[196:199], v[208:211], v[38:41]
	ds_read_b128 v[208:211], v0 offset:4096
	s_waitcnt lgkmcnt(5)
	v_mfma_f32_16x16x32_bf16 v[34:37], v[166:169], v[238:241], v[34:37]
	v_mfma_f32_16x16x32_bf16 v[30:33], v[170:173], v[238:241], v[30:33]
	v_mfma_f32_16x16x32_bf16 v[26:29], v[192:195], v[238:241], v[26:29]
	v_mfma_f32_16x16x32_bf16 v[22:25], v[196:199], v[238:241], v[22:25]
	ds_read_b128 v[238:241], v0 offset:6144
	s_waitcnt lgkmcnt(3)
	v_mfma_f32_16x16x32_bf16 v[158:161], v[212:215], v[162:165], v[158:161]
	v_mfma_f32_16x16x32_bf16 v[154:157], v[216:219], v[162:165], v[154:157]
	v_mfma_f32_16x16x32_bf16 v[150:153], v[220:223], v[162:165], v[150:153]
	v_mfma_f32_16x16x32_bf16 v[146:149], v[224:227], v[162:165], v[146:149]
	ds_read_b128 v[162:165], v0 offset:8192
	s_waitcnt lgkmcnt(3)
	v_mfma_f32_16x16x32_bf16 v[142:145], v[212:215], v[204:207], v[142:145]
	v_mfma_f32_16x16x32_bf16 v[138:141], v[216:219], v[204:207], v[138:141]
	v_mfma_f32_16x16x32_bf16 v[134:137], v[220:223], v[204:207], v[134:137]
	v_mfma_f32_16x16x32_bf16 v[130:133], v[224:227], v[204:207], v[130:133]
	ds_read_b128 v[204:207], v0 offset:10240
	s_waitcnt lgkmcnt(3)
	v_mfma_f32_16x16x32_bf16 v[126:129], v[212:215], v[208:211], v[126:129]
	v_mfma_f32_16x16x32_bf16 v[122:125], v[216:219], v[208:211], v[122:125]
	v_mfma_f32_16x16x32_bf16 v[118:121], v[220:223], v[208:211], v[118:121]
	v_mfma_f32_16x16x32_bf16 v[114:117], v[224:227], v[208:211], v[114:117]
	ds_read_b128 v[208:211], v0 offset:12288
	s_waitcnt lgkmcnt(3)
	v_mfma_f32_16x16x32_bf16 v[110:113], v[212:215], v[238:241], v[110:113]
	v_mfma_f32_16x16x32_bf16 v[106:109], v[216:219], v[238:241], v[106:109]
	v_mfma_f32_16x16x32_bf16 v[102:105], v[220:223], v[238:241], v[102:105]
	v_mfma_f32_16x16x32_bf16 v[98:101], v[224:227], v[238:241], v[98:101]
	ds_read_b128 v[238:241], v0 offset:14336
	s_waitcnt lgkmcnt(3)
	v_mfma_f32_16x16x32_bf16 v[94:97], v[212:215], v[162:165], v[94:97]
	v_mfma_f32_16x16x32_bf16 v[90:93], v[216:219], v[162:165], v[90:93]
	v_mfma_f32_16x16x32_bf16 v[86:89], v[220:223], v[162:165], v[86:89]
	v_mfma_f32_16x16x32_bf16 v[82:85], v[224:227], v[162:165], v[82:85]
	s_waitcnt vmcnt(0)
	s_waitcnt lgkmcnt(0)
	s_setprio 0
	s_barrier
; template <int MI, int NJ> ...
;     ...
;   for (int kt = 0; kt < nk; ++kt) {
;     const int buf = kt & 1;
;     {
;       G8STORE(buf ^ 1);
;       const u16* ga_ = (kt + 2 < nk) ? Ag + (kt + 2) * 64 : Ag + nAoff;
;       const u16* gb_ = (kt + 2 < nk) ? Bg + (kt + 2) * 64 : Bg + nBoff;
;       G8LOADP(ga_, gb_);
;     }
; __device__ __forceinline__ void phase_gemm_f32(const u16* A, const u16* Bt, int K, u16* out, u16* smem,
;                                                volatile LAS unsigned* vb_) {
;     ...
; #pragma unroll
;     for (int i = 0; i < 8; ++i)
; #pragma unroll
;       for (int j = 0; j < 4; ++j)
; #pragma unroll
;         for (int r = 0; r < 4; ++r)
;           smem[(wm * 128 + i * 16 + (lane >> 4) * 4 + r) * 264 + wn * 64 + j * 16 + (lane & 15)] = f2bf(acc[i][j][r]);
;     __syncthreads();
	s_add_i32 s44, s44, 1
	s_add_i32 s39, s39, 64
	s_addk_i32 s43, 0x4000
	s_and_b32 s45, s43, 0x4000
	s_sub_i32 s67, s39, 64
	s_add_i32 s46, s44, 1
	s_cmp_lt_u32 s46, s21
	s_cselect_b32 s47, 0, s12
	s_cselect_b32 s46, s67, s13
	s_cselect_b32 s49, 0, s37
	s_cselect_b32 s48, s67, s38
	s_lshl_b64 s[46:47], s[46:47], 1
	s_lshl_b64 s[48:49], s[48:49], 1
	s_add_u32 s50, s62, s46
	s_addc_u32 s51, s63, s47
	s_add_u32 s52, s64, s48
	s_addc_u32 s53, s65, s49
	s_lshl_b32 s45, s45, 1
	v_add_u32_e32 v0, s45, v187
	v_add_u32_e32 v191, s45, v188
	s_setprio 1
	ds_read_b128 v[166:169], v191
	ds_read_b128 v[162:165], v0
	ds_read_b128 v[170:173], v191 offset:2048
	ds_read_b128 v[192:195], v191 offset:4096
	ds_read_b128 v[196:199], v191 offset:6144
	v_mfma_f32_16x16x32_bf16 v[78:81], v[212:215], v[204:207], v[78:81]
	v_mfma_f32_16x16x32_bf16 v[70:73], v[216:219], v[204:207], v[70:73]
	v_mfma_f32_16x16x32_bf16 v[66:69], v[220:223], v[204:207], v[66:69]
	v_mfma_f32_16x16x32_bf16 v[58:61], v[224:227], v[204:207], v[58:61]
	ds_read_b128 v[204:207], v0 offset:2048
	v_mfma_f32_16x16x32_bf16 v[54:57], v[212:215], v[208:211], v[54:57]
	v_mfma_f32_16x16x32_bf16 v[50:53], v[216:219], v[208:211], v[50:53]
	v_mfma_f32_16x16x32_bf16 v[46:49], v[220:223], v[208:211], v[46:49]
	v_mfma_f32_16x16x32_bf16 v[38:41], v[224:227], v[208:211], v[38:41]
	ds_read_b128 v[208:211], v0 offset:4096
	v_mfma_f32_16x16x32_bf16 v[34:37], v[212:215], v[238:241], v[34:37]
	v_mfma_f32_16x16x32_bf16 v[30:33], v[216:219], v[238:241], v[30:33]
	v_mfma_f32_16x16x32_bf16 v[26:29], v[220:223], v[238:241], v[26:29]
	v_mfma_f32_16x16x32_bf16 v[22:25], v[224:227], v[238:241], v[22:25]
	ds_read_b128 v[238:241], v0 offset:6144
	v_add_u32_e32 v191, v191, v190
	s_setprio 0
	s_cmp_lg_u32 s21, s44
	s_cbranch_scc1 .LBB0_481
	v_and_b32_e32 v228, 15, v175
	v_bfe_u32 v229, v175, 8, 1
	v_lshl_or_b32 v228, v229, 7, v228
	v_mul_u32_u24_e32 v228, 0x210, v228
	v_bfe_u32 v229, v175, 6, 2
	v_lshl_add_u32 v228, v229, 7, v228
	v_bfe_u32 v229, v175, 4, 2
	v_lshl_add_u32 v228, v229, 3, v228
	v_cvt_pk_bf16_f32 v158, v158, v159
	v_cvt_pk_bf16_f32 v159, v160, v161
	v_cvt_pk_bf16_f32 v154, v154, v155
	v_cvt_pk_bf16_f32 v155, v156, v157
	v_cvt_pk_bf16_f32 v150, v150, v151
	v_cvt_pk_bf16_f32 v151, v152, v153
	v_cvt_pk_bf16_f32 v146, v146, v147
	v_cvt_pk_bf16_f32 v147, v148, v149
	ds_write_b64 v228, v[158:159]
	ds_write_b64 v228, v[154:155] offset:32
	ds_write_b64 v228, v[150:151] offset:64
	ds_write_b64 v228, v[146:147] offset:96
	v_cvt_pk_bf16_f32 v142, v142, v143
	v_cvt_pk_bf16_f32 v143, v144, v145
	v_cvt_pk_bf16_f32 v138, v138, v139
	v_cvt_pk_bf16_f32 v139, v140, v141
	v_cvt_pk_bf16_f32 v134, v134, v135
	v_cvt_pk_bf16_f32 v135, v136, v137
	v_cvt_pk_bf16_f32 v130, v130, v131
	v_cvt_pk_bf16_f32 v131, v132, v133
	ds_write_b64 v228, v[142:143] offset:8448
	ds_write_b64 v228, v[138:139] offset:8480
	ds_write_b64 v228, v[134:135] offset:8512
	ds_write_b64 v228, v[130:131] offset:8544
	v_cvt_pk_bf16_f32 v126, v126, v127
	v_cvt_pk_bf16_f32 v127, v128, v129
	v_cvt_pk_bf16_f32 v122, v122, v123
	v_cvt_pk_bf16_f32 v123, v124, v125
	v_cvt_pk_bf16_f32 v118, v118, v119
	v_cvt_pk_bf16_f32 v119, v120, v121
	v_cvt_pk_bf16_f32 v114, v114, v115
	v_cvt_pk_bf16_f32 v115, v116, v117
	ds_write_b64 v228, v[126:127] offset:16896
	ds_write_b64 v228, v[122:123] offset:16928
	ds_write_b64 v228, v[118:119] offset:16960
	ds_write_b64 v228, v[114:115] offset:16992
	v_cvt_pk_bf16_f32 v110, v110, v111
	v_cvt_pk_bf16_f32 v111, v112, v113
	v_cvt_pk_bf16_f32 v106, v106, v107
	v_cvt_pk_bf16_f32 v107, v108, v109
	v_cvt_pk_bf16_f32 v102, v102, v103
	v_cvt_pk_bf16_f32 v103, v104, v105
	v_cvt_pk_bf16_f32 v98, v98, v99
	v_cvt_pk_bf16_f32 v99, v100, v101
	ds_write_b64 v228, v[110:111] offset:25344
	ds_write_b64 v228, v[106:107] offset:25376
	ds_write_b64 v228, v[102:103] offset:25408
	ds_write_b64 v228, v[98:99] offset:25440
	v_cvt_pk_bf16_f32 v94, v94, v95
	v_cvt_pk_bf16_f32 v95, v96, v97
	v_cvt_pk_bf16_f32 v90, v90, v91
	v_cvt_pk_bf16_f32 v91, v92, v93
	v_cvt_pk_bf16_f32 v86, v86, v87
	v_cvt_pk_bf16_f32 v87, v88, v89
	v_cvt_pk_bf16_f32 v82, v82, v83
	v_cvt_pk_bf16_f32 v83, v84, v85
	ds_write_b64 v228, v[94:95] offset:33792
	ds_write_b64 v228, v[90:91] offset:33824
	ds_write_b64 v228, v[86:87] offset:33856
	ds_write_b64 v228, v[82:83] offset:33888
	v_cvt_pk_bf16_f32 v78, v78, v79
	v_cvt_pk_bf16_f32 v79, v80, v81
	v_cvt_pk_bf16_f32 v70, v70, v71
	v_cvt_pk_bf16_f32 v71, v72, v73
	v_cvt_pk_bf16_f32 v66, v66, v67
	v_cvt_pk_bf16_f32 v67, v68, v69
	v_cvt_pk_bf16_f32 v58, v58, v59
	v_cvt_pk_bf16_f32 v59, v60, v61
	ds_write_b64 v228, v[78:79] offset:42240
	ds_write_b64 v228, v[70:71] offset:42272
	ds_write_b64 v228, v[66:67] offset:42304
	ds_write_b64 v228, v[58:59] offset:42336
	v_cvt_pk_bf16_f32 v54, v54, v55
	v_cvt_pk_bf16_f32 v55, v56, v57
	v_cvt_pk_bf16_f32 v50, v50, v51
	v_cvt_pk_bf16_f32 v51, v52, v53
	v_cvt_pk_bf16_f32 v46, v46, v47
	v_cvt_pk_bf16_f32 v47, v48, v49
	v_cvt_pk_bf16_f32 v38, v38, v39
	v_cvt_pk_bf16_f32 v39, v40, v41
	ds_write_b64 v228, v[54:55] offset:50688
	ds_write_b64 v228, v[50:51] offset:50720
	ds_write_b64 v228, v[46:47] offset:50752
	ds_write_b64 v228, v[38:39] offset:50784
	v_cvt_pk_bf16_f32 v34, v34, v35
	v_cvt_pk_bf16_f32 v35, v36, v37
	v_cvt_pk_bf16_f32 v30, v30, v31
	v_cvt_pk_bf16_f32 v31, v32, v33
	v_cvt_pk_bf16_f32 v26, v26, v27
	v_cvt_pk_bf16_f32 v27, v28, v29
	v_cvt_pk_bf16_f32 v22, v22, v23
	v_cvt_pk_bf16_f32 v23, v24, v25
	ds_write_b64 v228, v[34:35] offset:59136
	ds_write_b64 v228, v[30:31] offset:59168
	ds_write_b64 v228, v[26:27] offset:59200
	ds_write_b64 v228, v[22:23] offset:59232
	s_ashr_i32 s43, s42, 31
	v_mov_b32_e32 v34, v175
	s_lshl_b64 s[12:13], s[42:43], 1
	s_waitcnt lgkmcnt(0)
	s_barrier
; #define RTID opaque_tid()
; __device__ __forceinline__ void phase_gemm_f32(const u16* A, const u16* Bt, int K, u16* out, u16* smem,
;                                                volatile LAS unsigned* vb_) {
;     ...
;     const int tid2 = RTID;
; #pragma unroll
;     for (int k = 0; k < 16; ++k) {
;       const int c = tid2 + 512 * k;
;       const int row = c >> 5, ch = c & 31;
;       const uint4 v = *(const uint4*)(smem + row * 264 + ch * 8);
;       *(uint4*)(out + (size_t)(mt * 256 + row) * 1024 + nt * 256 + ch * 8) = v;
;     }
;     __syncthreads();
;   }
	s_add_u32 s12, s11, s12
	v_lshlrev_b32_e32 v0, 4, v34
	v_and_b32_e32 v0, 0x1f0, v0
	s_addc_u32 s13, s20, s13
	v_ashrrev_i32_e32 v26, 5, v34
	v_lshl_add_u64 v[30:31], s[12:13], 0, v[0:1]
	v_mad_u64_u32 v[22:23], s[12:13], v26, s2, v[0:1]
	v_add_u32_e32 v26, s23, v26
	v_ashrrev_i32_e32 v27, 31, v26
	ds_read_b128 v[22:25], v22
	v_lshlrev_b64 v[26:27], 11, v[26:27]
	v_lshl_add_u64 v[32:33], v[30:31], 0, v[26:27]
	v_add_u32_e32 v26, 0x200, v34
	v_ashrrev_i32_e32 v35, 5, v26
	v_mad_u64_u32 v[26:27], s[12:13], v35, s2, v[0:1]
	ds_read_b128 v[26:29], v26
	s_waitcnt lgkmcnt(1)
	global_store_dwordx4 v[32:33], v[22:25], off
	s_and_b64 vcc, exec, s[40:41]
	s_mov_b32 s37, s36
	v_add_u32_e32 v22, s23, v35
	v_ashrrev_i32_e32 v23, 31, v22
	v_lshlrev_b64 v[22:23], 11, v[22:23]
	v_lshl_add_u64 v[22:23], v[30:31], 0, v[22:23]
	s_waitcnt lgkmcnt(0)
	global_store_dwordx4 v[22:23], v[26:29], off
	v_add_u32_e32 v22, 0x400, v34
	s_nop 0
	v_ashrrev_i32_e32 v26, 5, v22
	v_mad_u64_u32 v[22:23], s[12:13], v26, s2, v[0:1]
	v_add_u32_e32 v26, s23, v26
	v_ashrrev_i32_e32 v27, 31, v26
	ds_read_b128 v[22:25], v22
	v_lshlrev_b64 v[26:27], 11, v[26:27]
	v_lshl_add_u64 v[32:33], v[30:31], 0, v[26:27]
	v_add_u32_e32 v26, 0x600, v34
	v_ashrrev_i32_e32 v35, 5, v26
	v_mad_u64_u32 v[26:27], s[12:13], v35, s2, v[0:1]
	ds_read_b128 v[26:29], v26
	s_waitcnt lgkmcnt(1)
	global_store_dwordx4 v[32:33], v[22:25], off
	s_nop 1
	v_add_u32_e32 v22, s23, v35
	v_ashrrev_i32_e32 v23, 31, v22
	v_lshlrev_b64 v[22:23], 11, v[22:23]
	v_lshl_add_u64 v[22:23], v[30:31], 0, v[22:23]
	s_waitcnt lgkmcnt(0)
	global_store_dwordx4 v[22:23], v[26:29], off
	v_add_u32_e32 v22, 0x800, v34
	s_nop 0
	v_ashrrev_i32_e32 v26, 5, v22
	v_mad_u64_u32 v[22:23], s[12:13], v26, s2, v[0:1]
	v_add_u32_e32 v26, s23, v26
	v_ashrrev_i32_e32 v27, 31, v26
	ds_read_b128 v[22:25], v22
	v_lshlrev_b64 v[26:27], 11, v[26:27]
	v_lshl_add_u64 v[32:33], v[30:31], 0, v[26:27]
	v_add_u32_e32 v26, 0xa00, v34
	v_ashrrev_i32_e32 v35, 5, v26
	v_mad_u64_u32 v[26:27], s[12:13], v35, s2, v[0:1]
	ds_read_b128 v[26:29], v26
	s_waitcnt lgkmcnt(1)
	global_store_dwordx4 v[32:33], v[22:25], off
	s_nop 1
	v_add_u32_e32 v22, s23, v35
	v_ashrrev_i32_e32 v23, 31, v22
	v_lshlrev_b64 v[22:23], 11, v[22:23]
	v_lshl_add_u64 v[22:23], v[30:31], 0, v[22:23]
	s_waitcnt lgkmcnt(0)
	global_store_dwordx4 v[22:23], v[26:29], off
	v_add_u32_e32 v22, 0xc00, v34
	s_nop 0
	v_ashrrev_i32_e32 v26, 5, v22
	v_mad_u64_u32 v[22:23], s[12:13], v26, s2, v[0:1]
	v_add_u32_e32 v26, s23, v26
	v_ashrrev_i32_e32 v27, 31, v26
	ds_read_b128 v[22:25], v22
	v_lshlrev_b64 v[26:27], 11, v[26:27]
	v_lshl_add_u64 v[32:33], v[30:31], 0, v[26:27]
	v_add_u32_e32 v26, 0xe00, v34
	v_ashrrev_i32_e32 v35, 5, v26
	v_mad_u64_u32 v[26:27], s[12:13], v35, s2, v[0:1]
	ds_read_b128 v[26:29], v26
	s_waitcnt lgkmcnt(1)
	global_store_dwordx4 v[32:33], v[22:25], off
	s_nop 1
	v_add_u32_e32 v22, s23, v35
	v_ashrrev_i32_e32 v23, 31, v22
	v_lshlrev_b64 v[22:23], 11, v[22:23]
	v_lshl_add_u64 v[22:23], v[30:31], 0, v[22:23]
	s_waitcnt lgkmcnt(0)
	global_store_dwordx4 v[22:23], v[26:29], off
	v_add_u32_e32 v22, 0x1000, v34
	s_nop 0
	v_ashrrev_i32_e32 v26, 5, v22
	v_mad_u64_u32 v[22:23], s[12:13], v26, s2, v[0:1]
	v_add_u32_e32 v26, s23, v26
	v_ashrrev_i32_e32 v27, 31, v26
	ds_read_b128 v[22:25], v22
	v_lshlrev_b64 v[26:27], 11, v[26:27]
	v_lshl_add_u64 v[32:33], v[30:31], 0, v[26:27]
	v_add_u32_e32 v26, 0x1200, v34
	v_ashrrev_i32_e32 v35, 5, v26
	v_mad_u64_u32 v[26:27], s[12:13], v35, s2, v[0:1]
	ds_read_b128 v[26:29], v26
	s_waitcnt lgkmcnt(1)
	global_store_dwordx4 v[32:33], v[22:25], off
	s_nop 1
	v_add_u32_e32 v22, s23, v35
	v_ashrrev_i32_e32 v23, 31, v22
	v_lshlrev_b64 v[22:23], 11, v[22:23]
	v_lshl_add_u64 v[22:23], v[30:31], 0, v[22:23]
	s_waitcnt lgkmcnt(0)
	global_store_dwordx4 v[22:23], v[26:29], off
	v_add_u32_e32 v22, 0x1400, v34
	s_nop 0
	v_ashrrev_i32_e32 v26, 5, v22
	v_mad_u64_u32 v[22:23], s[12:13], v26, s2, v[0:1]
	v_add_u32_e32 v26, s23, v26
	v_ashrrev_i32_e32 v27, 31, v26
	ds_read_b128 v[22:25], v22
	v_lshlrev_b64 v[26:27], 11, v[26:27]
	v_lshl_add_u64 v[32:33], v[30:31], 0, v[26:27]
	v_add_u32_e32 v26, 0x1600, v34
	v_ashrrev_i32_e32 v35, 5, v26
	v_mad_u64_u32 v[26:27], s[12:13], v35, s2, v[0:1]
	ds_read_b128 v[26:29], v26
	s_waitcnt lgkmcnt(1)
	global_store_dwordx4 v[32:33], v[22:25], off
	s_nop 1
	v_add_u32_e32 v22, s23, v35
	v_ashrrev_i32_e32 v23, 31, v22
	v_lshlrev_b64 v[22:23], 11, v[22:23]
	v_lshl_add_u64 v[22:23], v[30:31], 0, v[22:23]
	s_waitcnt lgkmcnt(0)
	global_store_dwordx4 v[22:23], v[26:29], off
	v_add_u32_e32 v22, 0x1800, v34
	s_nop 0
	v_ashrrev_i32_e32 v26, 5, v22
	v_mad_u64_u32 v[22:23], s[12:13], v26, s2, v[0:1]
	v_add_u32_e32 v26, s23, v26
	v_ashrrev_i32_e32 v27, 31, v26
	ds_read_b128 v[22:25], v22
	v_lshlrev_b64 v[26:27], 11, v[26:27]
	v_lshl_add_u64 v[32:33], v[30:31], 0, v[26:27]
	v_add_u32_e32 v26, 0x1a00, v34
	v_ashrrev_i32_e32 v35, 5, v26
	v_mad_u64_u32 v[26:27], s[12:13], v35, s2, v[0:1]
	ds_read_b128 v[26:29], v26
	s_waitcnt lgkmcnt(1)
	global_store_dwordx4 v[32:33], v[22:25], off
	s_nop 1
	v_add_u32_e32 v22, s23, v35
	v_ashrrev_i32_e32 v23, 31, v22
	v_lshlrev_b64 v[22:23], 11, v[22:23]
	v_lshl_add_u64 v[22:23], v[30:31], 0, v[22:23]
	s_waitcnt lgkmcnt(0)
	global_store_dwordx4 v[22:23], v[26:29], off
	v_add_u32_e32 v22, 0x1c00, v34
	s_nop 0
	v_ashrrev_i32_e32 v26, 5, v22
	v_mad_u64_u32 v[22:23], s[12:13], v26, s2, v[0:1]
	v_add_u32_e32 v26, s23, v26
	v_ashrrev_i32_e32 v27, 31, v26
	ds_read_b128 v[22:25], v22
	v_lshlrev_b64 v[26:27], 11, v[26:27]
	v_lshl_add_u64 v[32:33], v[30:31], 0, v[26:27]
	v_add_u32_e32 v26, 0x1e00, v34
	v_ashrrev_i32_e32 v34, 5, v26
	v_mad_u64_u32 v[26:27], s[12:13], v34, s2, v[0:1]
	ds_read_b128 v[26:29], v26
	s_waitcnt lgkmcnt(1)
	global_store_dwordx4 v[32:33], v[22:25], off
	s_mov_b64 s[12:13], -1
	s_nop 0
	v_add_u32_e32 v22, s23, v34
	v_ashrrev_i32_e32 v23, 31, v22
	v_lshlrev_b64 v[22:23], 11, v[22:23]
	v_lshl_add_u64 v[22:23], v[30:31], 0, v[22:23]
	s_waitcnt lgkmcnt(0)
	global_store_dwordx4 v[22:23], v[26:29], off
	s_barrier
	s_cbranch_vccz .LBB0_478
